# MLA loop: issue the first QK MFMA of each tile before any softmax VALU
# baseline (speedup 1.0000x reference)
.Lmf_loop:
	ds_read_b128 v[162:165], v216 offset:13312
	ds_read_b128 v[166:169], v216 offset:19968
	ds_read_b128 v[172:175], v216 offset:13344
	ds_read_b128 v[176:179], v216 offset:20000
	ds_read_b128 v[180:183], v216 offset:13376
	global_load_dwordx4 v[130:133], v235, s[14:15]
	global_load_dwordx4 v[134:137], v236, s[14:15]
	s_add_u32 s14, s14, 0x18000
	s_addc_u32 s15, s15, 0
	global_load_dwordx4 v[142:145], v237, s[12:13]
	s_add_u32 s12, s12, 0x80
	s_addc_u32 s13, s13, 0
	s_waitcnt lgkmcnt(4)
	v_mfma_f32_32x32x16_bf16 v[34:49], v[162:165], v[98:101], v[146:161]
	ds_read_b128 v[184:187], v216 offset:20032
	v_exp_f32_e32 v66, v66
	v_exp_f32_e32 v67, v67
	v_exp_f32_e32 v68, v68
	v_exp_f32_e32 v69, v69
	s_waitcnt lgkmcnt(4)
	v_mfma_f32_32x32x16_bf16 v[50:65], v[166:169], v[98:101], v[146:161]
	ds_read_b128 v[188:191], v216 offset:13408
	v_add_f32_e32 v171, v66, v171
	v_exp_f32_e32 v70, v70
	v_exp_f32_e32 v71, v71
	v_add_f32_e32 v171, v68, v171
	s_waitcnt lgkmcnt(4)
	v_mfma_f32_32x32x16_bf16 v[34:49], v[172:175], v[102:105], v[34:49]
	ds_read_b128 v[192:195], v216 offset:20064
	v_exp_f32_e32 v72, v72
	v_add_f32_e32 v197, v67, v69
	v_exp_f32_e32 v73, v73
	v_add_f32_e32 v171, v70, v171
	s_waitcnt lgkmcnt(4)
	v_mfma_f32_32x32x16_bf16 v[50:65], v[176:179], v[102:105], v[50:65]
	ds_read_b128 v[162:165], v216 offset:13440
	v_add_f32_e32 v197, v71, v197
	v_cvt_pk_bf16_f32 v66, v66, v67
	v_add_f32_e32 v171, v72, v171
	v_cvt_pk_bf16_f32 v67, v68, v69
	v_add_f32_e32 v197, v73, v197
	v_cvt_pk_bf16_f32 v68, v70, v71
	v_cvt_pk_bf16_f32 v69, v72, v73
	s_waitcnt lgkmcnt(4)
	v_mfma_f32_32x32x16_bf16 v[34:49], v[180:183], v[106:109], v[34:49]
	ds_read_b128 v[166:169], v216 offset:20096
	v_exp_f32_e32 v74, v74
	v_exp_f32_e32 v75, v75
	v_exp_f32_e32 v76, v76
	s_waitcnt lgkmcnt(4)
	v_mfma_f32_32x32x16_bf16 v[50:65], v[184:187], v[106:109], v[50:65]
	ds_read_b128 v[172:175], v216 offset:13472
	v_exp_f32_e32 v77, v77
	v_add_f32_e32 v171, v74, v171
	v_exp_f32_e32 v78, v78
	v_add_f32_e32 v197, v75, v197
	v_exp_f32_e32 v79, v79
	s_waitcnt lgkmcnt(4)
	v_mfma_f32_32x32x16_bf16 v[34:49], v[188:191], v[110:113], v[34:49]
	ds_read_b128 v[176:179], v216 offset:20128
	v_add_f32_e32 v171, v76, v171
	v_exp_f32_e32 v80, v80
	v_add_f32_e32 v197, v77, v197
	v_exp_f32_e32 v81, v81
	s_waitcnt lgkmcnt(4)
	v_mfma_f32_32x32x16_bf16 v[50:65], v[192:195], v[110:113], v[50:65]
	ds_read_b128 v[180:183], v217 offset:26624
	v_add_f32_e32 v171, v78, v171
	v_add_f32_e32 v197, v79, v197
	v_cvt_pk_bf16_f32 v74, v74, v75
	v_add_f32_e32 v171, v80, v171
	v_cvt_pk_bf16_f32 v75, v76, v77
	v_add_f32_e32 v197, v81, v197
	s_waitcnt lgkmcnt(4)
	v_mfma_f32_32x32x16_bf16 v[34:49], v[162:165], v[114:117], v[34:49]
	ds_read_b128 v[184:187], v217 offset:31232
	v_cvt_pk_bf16_f32 v76, v78, v79
	v_cvt_pk_bf16_f32 v77, v80, v81
	v_exp_f32_e32 v82, v82
	v_exp_f32_e32 v83, v83
	v_exp_f32_e32 v84, v84
	s_waitcnt lgkmcnt(4)
	v_mfma_f32_32x32x16_bf16 v[50:65], v[166:169], v[114:117], v[50:65]
	ds_read_b128 v[188:191], v217 offset:26656
	v_exp_f32_e32 v85, v85
	v_add_f32_e32 v171, v82, v171
	v_exp_f32_e32 v86, v86
	s_waitcnt lgkmcnt(4)
	v_mfma_f32_32x32x16_bf16 v[34:49], v[172:175], v[118:121], v[34:49]
	ds_read_b128 v[192:195], v217 offset:31264
	v_add_f32_e32 v197, v83, v197
	v_exp_f32_e32 v87, v87
	v_add_f32_e32 v171, v84, v171
	v_exp_f32_e32 v88, v88
	v_add_f32_e32 v197, v85, v197
	s_waitcnt lgkmcnt(4)
	v_mfma_f32_32x32x16_bf16 v[50:65], v[176:179], v[118:121], v[50:65]
	ds_read_b128 v[162:165], v217 offset:26688
	v_exp_f32_e32 v89, v89
	v_add_f32_e32 v171, v86, v171
	v_add_f32_e32 v197, v87, v197
	v_cvt_pk_bf16_f32 v82, v82, v83
	v_add_f32_e32 v171, v88, v171
	s_waitcnt lgkmcnt(4)
	v_mfma_f32_32x32x16_bf16 v[18:33], v[180:183], v[66:69], v[18:33]
	ds_read_b128 v[166:169], v217 offset:31296
	v_cvt_pk_bf16_f32 v83, v84, v85
	v_add_f32_e32 v197, v89, v197
	v_cvt_pk_bf16_f32 v84, v86, v87
	v_cvt_pk_bf16_f32 v85, v88, v89
	v_exp_f32_e32 v90, v90
	v_exp_f32_e32 v91, v91
	s_waitcnt lgkmcnt(4)
	v_mfma_f32_32x32x16_bf16 v[2:17], v[184:187], v[66:69], v[2:17]
	ds_read_b128 v[172:175], v217 offset:26720
	v_exp_f32_e32 v92, v92
	v_exp_f32_e32 v93, v93
	v_add_f32_e32 v171, v90, v171
	v_exp_f32_e32 v94, v94
	s_waitcnt lgkmcnt(4)
	v_mfma_f32_32x32x16_bf16 v[18:33], v[188:191], v[74:77], v[18:33]
	ds_read_b128 v[176:179], v217 offset:31328
	v_add_f32_e32 v197, v91, v197
	v_exp_f32_e32 v95, v95
	v_add_f32_e32 v171, v92, v171
	v_exp_f32_e32 v96, v96
	s_waitcnt lgkmcnt(4)
	v_mfma_f32_32x32x16_bf16 v[2:17], v[192:195], v[74:77], v[2:17]
	s_waitcnt vmcnt(3)
	v_add_u32_e32 v196, 0x8800, v215
	ds_write_b128 v228, v[122:125]
	ds_write_b128 v238, v[126:129]
	ds_write2_b64 v196, v[138:139], v[140:141] offset0:128 offset1:130
	v_add_f32_e32 v197, v93, v197
	v_exp_f32_e32 v97, v97
	v_add_f32_e32 v171, v94, v171
	v_add_f32_e32 v197, v95, v197
	v_cvt_pk_bf16_f32 v90, v90, v91
	s_waitcnt lgkmcnt(6)
	v_mfma_f32_32x32x16_bf16 v[18:33], v[162:165], v[82:85], v[18:33]
	v_add_f32_e32 v171, v96, v171
	v_cvt_pk_bf16_f32 v91, v92, v93
	v_add_f32_e32 v197, v97, v197
	v_cvt_pk_bf16_f32 v92, v94, v95
	v_cvt_pk_bf16_f32 v93, v96, v97
	v_max3_f32 v1, v34, v35, v36
	s_waitcnt lgkmcnt(5)
	v_mfma_f32_32x32x16_bf16 v[2:17], v[166:169], v[82:85], v[2:17]
	v_max3_f32 v170, v37, v38, v39
	v_max3_f32 v1, v1, v40, v41
	v_max3_f32 v170, v170, v42, v43
	v_max3_f32 v1, v1, v44, v45
	v_max3_f32 v170, v170, v46, v47
	v_max3_f32 v1, v1, v48, v49
	v_max3_f32 v170, v170, v50, v51
	s_waitcnt lgkmcnt(4)
	v_mfma_f32_32x32x16_bf16 v[18:33], v[172:175], v[90:93], v[18:33]
	v_max3_f32 v1, v1, v52, v53
	v_max3_f32 v170, v170, v54, v55
	v_max3_f32 v1, v1, v56, v57
	v_max3_f32 v170, v170, v58, v59
	v_max3_f32 v1, v1, v60, v61
	v_max3_f32 v170, v170, v62, v63
	s_waitcnt lgkmcnt(3)
	v_mfma_f32_32x32x16_bf16 v[2:17], v[176:179], v[90:93], v[2:17]
	v_max3_f32 v1, v1, v64, v65
	v_max_f32_e32 v1, v1, v170
	v_mov_b32_e32 v170, v1
	v_add_f32_e32 v171, v197, v171
	s_nop 0
	v_permlane32_swap_b32_e32 v1, v170
	v_max_f32_e32 v1, v1, v170
	v_cmp_lt_f32_e32 vcc, s93, v1
	s_cbranch_vccnz .Lmf_slow_0
.Lmf_join_0:
	s_waitcnt lgkmcnt(0)
	s_barrier
	ds_read_b128 v[162:165], v216 offset:0
	ds_read_b128 v[166:169], v216 offset:6656
	ds_read_b128 v[172:175], v216 offset:32
	ds_read_b128 v[176:179], v216 offset:6688
	ds_read_b128 v[180:183], v216 offset:64
	global_load_dwordx4 v[122:125], v235, s[14:15]
	global_load_dwordx4 v[126:129], v236, s[14:15]
	s_add_u32 s14, s14, 0x18000
	s_addc_u32 s15, s15, 0
	global_load_dwordx4 v[138:141], v237, s[12:13]
	s_add_u32 s12, s12, 0x80
	s_addc_u32 s13, s13, 0
	s_waitcnt lgkmcnt(4)
	v_mfma_f32_32x32x16_bf16 v[66:81], v[162:165], v[98:101], v[146:161]
	ds_read_b128 v[184:187], v216 offset:6720
	v_exp_f32_e32 v34, v34
	v_exp_f32_e32 v35, v35
	v_exp_f32_e32 v36, v36
	v_exp_f32_e32 v37, v37
	s_waitcnt lgkmcnt(4)
	v_mfma_f32_32x32x16_bf16 v[82:97], v[166:169], v[98:101], v[146:161]
	ds_read_b128 v[188:191], v216 offset:96
	v_add_f32_e32 v171, v34, v171
	v_exp_f32_e32 v38, v38
	v_exp_f32_e32 v39, v39
	v_add_f32_e32 v171, v36, v171
	s_waitcnt lgkmcnt(4)
	v_mfma_f32_32x32x16_bf16 v[66:81], v[172:175], v[102:105], v[66:81]
	ds_read_b128 v[192:195], v216 offset:6752
	v_exp_f32_e32 v40, v40
	v_add_f32_e32 v197, v35, v37
	v_exp_f32_e32 v41, v41
	v_add_f32_e32 v171, v38, v171
	s_waitcnt lgkmcnt(4)
	v_mfma_f32_32x32x16_bf16 v[82:97], v[176:179], v[102:105], v[82:97]
	ds_read_b128 v[162:165], v216 offset:128
	v_add_f32_e32 v197, v39, v197
	v_cvt_pk_bf16_f32 v34, v34, v35
	v_add_f32_e32 v171, v40, v171
	v_cvt_pk_bf16_f32 v35, v36, v37
	v_add_f32_e32 v197, v41, v197
	v_cvt_pk_bf16_f32 v36, v38, v39
	v_cvt_pk_bf16_f32 v37, v40, v41
	s_waitcnt lgkmcnt(4)
	v_mfma_f32_32x32x16_bf16 v[66:81], v[180:183], v[106:109], v[66:81]
	ds_read_b128 v[166:169], v216 offset:6784
	v_exp_f32_e32 v42, v42
	v_exp_f32_e32 v43, v43
	v_exp_f32_e32 v44, v44
	s_waitcnt lgkmcnt(4)
	v_mfma_f32_32x32x16_bf16 v[82:97], v[184:187], v[106:109], v[82:97]
	ds_read_b128 v[172:175], v216 offset:160
	v_exp_f32_e32 v45, v45
	v_add_f32_e32 v171, v42, v171
	v_exp_f32_e32 v46, v46
	v_add_f32_e32 v197, v43, v197
	v_exp_f32_e32 v47, v47
	s_waitcnt lgkmcnt(4)
	v_mfma_f32_32x32x16_bf16 v[66:81], v[188:191], v[110:113], v[66:81]
	ds_read_b128 v[176:179], v216 offset:6816
	v_add_f32_e32 v171, v44, v171
	v_exp_f32_e32 v48, v48
	v_add_f32_e32 v197, v45, v197
	v_exp_f32_e32 v49, v49
	s_waitcnt lgkmcnt(4)
	v_mfma_f32_32x32x16_bf16 v[82:97], v[192:195], v[110:113], v[82:97]
	ds_read_b128 v[180:183], v217 offset:35840
	v_add_f32_e32 v171, v46, v171
	v_add_f32_e32 v197, v47, v197
	v_cvt_pk_bf16_f32 v42, v42, v43
	v_add_f32_e32 v171, v48, v171
	v_cvt_pk_bf16_f32 v43, v44, v45
	v_add_f32_e32 v197, v49, v197
	s_waitcnt lgkmcnt(4)
	v_mfma_f32_32x32x16_bf16 v[66:81], v[162:165], v[114:117], v[66:81]
	ds_read_b128 v[184:187], v217 offset:40448
	v_cvt_pk_bf16_f32 v44, v46, v47
	v_cvt_pk_bf16_f32 v45, v48, v49
	v_exp_f32_e32 v50, v50
	v_exp_f32_e32 v51, v51
	v_exp_f32_e32 v52, v52
	s_waitcnt lgkmcnt(4)
	v_mfma_f32_32x32x16_bf16 v[82:97], v[166:169], v[114:117], v[82:97]
	ds_read_b128 v[188:191], v217 offset:35872
	v_exp_f32_e32 v53, v53
	v_add_f32_e32 v171, v50, v171
	v_exp_f32_e32 v54, v54
	s_waitcnt lgkmcnt(4)
	v_mfma_f32_32x32x16_bf16 v[66:81], v[172:175], v[118:121], v[66:81]
	ds_read_b128 v[192:195], v217 offset:40480
	v_add_f32_e32 v197, v51, v197
	v_exp_f32_e32 v55, v55
	v_add_f32_e32 v171, v52, v171
	v_exp_f32_e32 v56, v56
	v_add_f32_e32 v197, v53, v197
	s_waitcnt lgkmcnt(4)
	v_mfma_f32_32x32x16_bf16 v[82:97], v[176:179], v[118:121], v[82:97]
	ds_read_b128 v[162:165], v217 offset:35904
	v_exp_f32_e32 v57, v57
	v_add_f32_e32 v171, v54, v171
	v_add_f32_e32 v197, v55, v197
	v_cvt_pk_bf16_f32 v50, v50, v51
	v_add_f32_e32 v171, v56, v171
	s_waitcnt lgkmcnt(4)
	v_mfma_f32_32x32x16_bf16 v[18:33], v[180:183], v[34:37], v[18:33]
	ds_read_b128 v[166:169], v217 offset:40512
	v_cvt_pk_bf16_f32 v51, v52, v53
	v_add_f32_e32 v197, v57, v197
	v_cvt_pk_bf16_f32 v52, v54, v55
	v_cvt_pk_bf16_f32 v53, v56, v57
	v_exp_f32_e32 v58, v58
	v_exp_f32_e32 v59, v59
	s_waitcnt lgkmcnt(4)
	v_mfma_f32_32x32x16_bf16 v[2:17], v[184:187], v[34:37], v[2:17]
	ds_read_b128 v[172:175], v217 offset:35936
	v_exp_f32_e32 v60, v60
	v_exp_f32_e32 v61, v61
	v_add_f32_e32 v171, v58, v171
	v_exp_f32_e32 v62, v62
	s_waitcnt lgkmcnt(4)
	v_mfma_f32_32x32x16_bf16 v[18:33], v[188:191], v[42:45], v[18:33]
	ds_read_b128 v[176:179], v217 offset:40544
	v_add_f32_e32 v197, v59, v197
	v_exp_f32_e32 v63, v63
	v_add_f32_e32 v171, v60, v171
	v_exp_f32_e32 v64, v64
	s_waitcnt lgkmcnt(4)
	v_mfma_f32_32x32x16_bf16 v[2:17], v[192:195], v[42:45], v[2:17]
	s_waitcnt vmcnt(3)
	ds_write_b128 v228, v[130:133] offset:13312
	ds_write_b128 v238, v[134:137] offset:13312
	ds_write2_b64 v225, v[142:143], v[144:145] offset1:2
	v_add_f32_e32 v197, v61, v197
	v_exp_f32_e32 v65, v65
	v_add_f32_e32 v171, v62, v171
	v_add_f32_e32 v197, v63, v197
	v_cvt_pk_bf16_f32 v58, v58, v59
	s_waitcnt lgkmcnt(6)
	v_mfma_f32_32x32x16_bf16 v[18:33], v[162:165], v[50:53], v[18:33]
	v_add_f32_e32 v171, v64, v171
	v_cvt_pk_bf16_f32 v59, v60, v61
	v_add_f32_e32 v197, v65, v197
	v_cvt_pk_bf16_f32 v60, v62, v63
	v_cvt_pk_bf16_f32 v61, v64, v65
	v_max3_f32 v1, v66, v67, v68
	s_waitcnt lgkmcnt(5)
	v_mfma_f32_32x32x16_bf16 v[2:17], v[166:169], v[50:53], v[2:17]
	v_max3_f32 v170, v69, v70, v71
	v_max3_f32 v1, v1, v72, v73
	v_max3_f32 v170, v170, v74, v75
	v_max3_f32 v1, v1, v76, v77
	v_max3_f32 v170, v170, v78, v79
	v_max3_f32 v1, v1, v80, v81
	v_max3_f32 v170, v170, v82, v83
	s_waitcnt lgkmcnt(4)
	v_mfma_f32_32x32x16_bf16 v[18:33], v[172:175], v[58:61], v[18:33]
	v_max3_f32 v1, v1, v84, v85
	v_max3_f32 v170, v170, v86, v87
	v_max3_f32 v1, v1, v88, v89
	v_max3_f32 v170, v170, v90, v91
	v_max3_f32 v1, v1, v92, v93
	v_max3_f32 v170, v170, v94, v95
	s_waitcnt lgkmcnt(3)
	v_mfma_f32_32x32x16_bf16 v[2:17], v[176:179], v[58:61], v[2:17]
	v_max3_f32 v1, v1, v96, v97
	v_max_f32_e32 v1, v1, v170
	v_mov_b32_e32 v170, v1
	v_add_f32_e32 v171, v197, v171
	s_nop 0
	v_permlane32_swap_b32_e32 v1, v170
	v_max_f32_e32 v1, v1, v170
	v_cmp_lt_f32_e32 vcc, s93, v1
	s_cbranch_vccnz .Lmf_slow_1
